# plain GEMM 16x16x32: mid-tile barrier moved 8 MFMAs later (operands already in registers) so LDS-read latency hides; DMA issue one per MFMA after it
# baseline (speedup 1.0000x reference)
; #define RAWBAR() { asm volatile("s_waitcnt vmcnt(0) lgkmcnt(0)" ::: "memory"); __builtin_amdgcn_s_barrier(); }
;     ...
;   if (V != 1) GLDS(0, 0);
;   RAWBAR();
;   for (int kt = 0; kt < nk; kt += 2) {
;     if (V != 1) GLDS(kt + 1, 1);
;     if (V != 2) COMPUTE(0);
;     RAWBAR();
;     if (V != 1) if (kt + 2 < nk) GLDS(kt + 2, 0);
;     if (V != 2) COMPUTE(1);
;     RAWBAR();
.Lgm_tile:
	s_waitcnt lgkmcnt(8)
	v_mfma_f32_16x16x32_bf16 v[0:3], v[162:165], v[128:131], 0
	v_mfma_f32_16x16x32_bf16 v[4:7], v[166:169], v[128:131], 0
	v_mfma_f32_16x16x32_bf16 v[8:11], v[170:173], v[128:131], 0
	v_mfma_f32_16x16x32_bf16 v[12:15], v[174:177], v[128:131], 0
	ds_read_b128 v[128:131], v205
	v_mfma_f32_16x16x32_bf16 v[16:19], v[162:165], v[132:135], 0
	v_mfma_f32_16x16x32_bf16 v[20:23], v[166:169], v[132:135], 0
	v_mfma_f32_16x16x32_bf16 v[24:27], v[170:173], v[132:135], 0
	v_mfma_f32_16x16x32_bf16 v[28:31], v[174:177], v[132:135], 0
	ds_read_b128 v[132:135], v205 offset:2048
	v_mfma_f32_16x16x32_bf16 v[32:35], v[162:165], v[136:139], 0
	v_mfma_f32_16x16x32_bf16 v[36:39], v[166:169], v[136:139], 0
	v_mfma_f32_16x16x32_bf16 v[40:43], v[170:173], v[136:139], 0
	v_mfma_f32_16x16x32_bf16 v[44:47], v[174:177], v[136:139], 0
	ds_read_b128 v[136:139], v205 offset:4096
	v_mfma_f32_16x16x32_bf16 v[48:51], v[162:165], v[140:143], 0
	v_mfma_f32_16x16x32_bf16 v[52:55], v[166:169], v[140:143], 0
	v_mfma_f32_16x16x32_bf16 v[56:59], v[170:173], v[140:143], 0
	v_mfma_f32_16x16x32_bf16 v[60:63], v[174:177], v[140:143], 0
	ds_read_b128 v[140:143], v205 offset:6144
	s_waitcnt lgkmcnt(8)
	v_mfma_f32_16x16x32_bf16 v[64:67], v[162:165], v[144:147], 0
	v_mfma_f32_16x16x32_bf16 v[68:71], v[166:169], v[144:147], 0
	v_mfma_f32_16x16x32_bf16 v[72:75], v[170:173], v[144:147], 0
	v_mfma_f32_16x16x32_bf16 v[76:79], v[174:177], v[144:147], 0
	ds_read_b128 v[144:147], v205 offset:8192
	v_mfma_f32_16x16x32_bf16 v[80:83], v[162:165], v[148:151], 0
	v_mfma_f32_16x16x32_bf16 v[84:87], v[166:169], v[148:151], 0
	v_mfma_f32_16x16x32_bf16 v[88:91], v[170:173], v[148:151], 0
	v_mfma_f32_16x16x32_bf16 v[92:95], v[174:177], v[148:151], 0
	ds_read_b128 v[148:151], v205 offset:10240
	v_mfma_f32_16x16x32_bf16 v[96:99], v[162:165], v[152:155], 0
	v_mfma_f32_16x16x32_bf16 v[100:103], v[166:169], v[152:155], 0
	v_mfma_f32_16x16x32_bf16 v[104:107], v[170:173], v[152:155], 0
	v_mfma_f32_16x16x32_bf16 v[108:111], v[174:177], v[152:155], 0
	ds_read_b128 v[152:155], v205 offset:12288
	v_mfma_f32_16x16x32_bf16 v[112:115], v[162:165], v[156:159], 0
	v_mfma_f32_16x16x32_bf16 v[116:119], v[166:169], v[156:159], 0
	v_mfma_f32_16x16x32_bf16 v[120:123], v[170:173], v[156:159], 0
	v_mfma_f32_16x16x32_bf16 v[124:127], v[174:177], v[156:159], 0
	ds_read_b128 v[156:159], v205 offset:14336
	s_waitcnt lgkmcnt(4)
	v_mfma_f32_16x16x32_bf16 v[0:3], v[224:227], v[128:131], v[0:3]
	v_mfma_f32_16x16x32_bf16 v[4:7], v[228:231], v[128:131], v[4:7]
	v_mfma_f32_16x16x32_bf16 v[8:11], v[232:235], v[128:131], v[8:11]
	v_mfma_f32_16x16x32_bf16 v[12:15], v[236:239], v[128:131], v[12:15]
	v_mfma_f32_16x16x32_bf16 v[16:19], v[224:227], v[132:135], v[16:19]
	v_mfma_f32_16x16x32_bf16 v[20:23], v[228:231], v[132:135], v[20:23]
	v_mfma_f32_16x16x32_bf16 v[24:27], v[232:235], v[132:135], v[24:27]
	v_mfma_f32_16x16x32_bf16 v[28:31], v[236:239], v[132:135], v[28:31]
	s_waitcnt vmcnt(0) lgkmcnt(0)
	s_barrier
	ds_read_b128 v[162:165], v210
	ds_read_b128 v[166:169], v210 offset:2048
	ds_read_b128 v[170:173], v210 offset:4096
	ds_read_b128 v[174:177], v210 offset:6144
	ds_read_b128 v[128:131], v206
	ds_read_b128 v[132:135], v206 offset:2048
	s_add_u32 m0, s14, 0x0
	v_mfma_f32_16x16x32_bf16 v[32:35], v[224:227], v[136:139], v[32:35]
	global_load_lds_dwordx4 v220, s[22:23]
	s_add_u32 m0, s14, 0x8000
	v_mfma_f32_16x16x32_bf16 v[36:39], v[228:231], v[136:139], v[36:39]
	global_load_lds_dwordx4 v220, s[24:25]
	s_add_u32 m0, s14, 0x400
	v_mfma_f32_16x16x32_bf16 v[40:43], v[232:235], v[136:139], v[40:43]
	global_load_lds_dwordx4 v221, s[22:23]
	s_add_u32 m0, s14, 0x8400
	v_mfma_f32_16x16x32_bf16 v[44:47], v[236:239], v[136:139], v[44:47]
	global_load_lds_dwordx4 v221, s[24:25]
	ds_read_b128 v[136:139], v206 offset:4096
	s_add_u32 m0, s14, 0x800
	v_mfma_f32_16x16x32_bf16 v[48:51], v[224:227], v[140:143], v[48:51]
	global_load_lds_dwordx4 v222, s[22:23]
	s_add_u32 m0, s14, 0x8800
	v_mfma_f32_16x16x32_bf16 v[52:55], v[228:231], v[140:143], v[52:55]
	global_load_lds_dwordx4 v222, s[24:25]
	s_add_u32 m0, s14, 0xc00
	v_mfma_f32_16x16x32_bf16 v[56:59], v[232:235], v[140:143], v[56:59]
	global_load_lds_dwordx4 v223, s[22:23]
	s_add_u32 m0, s14, 0x8c00
	v_mfma_f32_16x16x32_bf16 v[60:63], v[236:239], v[140:143], v[60:63]
	global_load_lds_dwordx4 v223, s[24:25]
	ds_read_b128 v[140:143], v206 offset:6144
	v_mfma_f32_16x16x32_bf16 v[64:67], v[224:227], v[144:147], v[64:67]
	v_mfma_f32_16x16x32_bf16 v[68:71], v[228:231], v[144:147], v[68:71]
	v_mfma_f32_16x16x32_bf16 v[72:75], v[232:235], v[144:147], v[72:75]
	v_mfma_f32_16x16x32_bf16 v[76:79], v[236:239], v[144:147], v[76:79]
	ds_read_b128 v[144:147], v206 offset:8192
	v_mfma_f32_16x16x32_bf16 v[80:83], v[224:227], v[148:151], v[80:83]
	v_mfma_f32_16x16x32_bf16 v[84:87], v[228:231], v[148:151], v[84:87]
	v_mfma_f32_16x16x32_bf16 v[88:91], v[232:235], v[148:151], v[88:91]
	v_mfma_f32_16x16x32_bf16 v[92:95], v[236:239], v[148:151], v[92:95]
	ds_read_b128 v[148:151], v206 offset:10240
	v_mfma_f32_16x16x32_bf16 v[96:99], v[224:227], v[152:155], v[96:99]
	v_mfma_f32_16x16x32_bf16 v[100:103], v[228:231], v[152:155], v[100:103]
	v_mfma_f32_16x16x32_bf16 v[104:107], v[232:235], v[152:155], v[104:107]
	v_mfma_f32_16x16x32_bf16 v[108:111], v[236:239], v[152:155], v[108:111]
	ds_read_b128 v[152:155], v206 offset:12288
	v_mfma_f32_16x16x32_bf16 v[112:115], v[224:227], v[156:159], v[112:115]
	v_mfma_f32_16x16x32_bf16 v[116:119], v[228:231], v[156:159], v[116:119]
	v_mfma_f32_16x16x32_bf16 v[120:123], v[232:235], v[156:159], v[120:123]
	v_mfma_f32_16x16x32_bf16 v[124:127], v[236:239], v[156:159], v[124:127]
	ds_read_b128 v[156:159], v206 offset:14336
	ds_read_b128 v[224:227], v211
	ds_read_b128 v[228:231], v211 offset:2048
	ds_read_b128 v[232:235], v211 offset:4096
	ds_read_b128 v[236:239], v211 offset:6144
	s_add_u32 s22, s22, 0x80
	s_addc_u32 s23, s23, 0
	s_add_u32 s24, s24, 0x80
	s_addc_u32 s25, s25, 0
	s_add_u32 s26, s26, 1
	s_cmp_eq_u32 s26, s50
	s_cbranch_scc0 .Lgm_cadv_done3
	s_mov_b32 s26, 0
	s_add_u32 s27, s27, s30
	s_cmp_lt_u32 s27, s29
	s_cbranch_scc1 .Lgm_cadv_new3
	s_lshl_b32 s53, s50, 7
	s_sub_u32 s22, s22, s53
	s_subb_u32 s23, s23, 0
	s_sub_u32 s24, s24, s53
	s_subb_u32 s25, s25, 0
	s_branch .Lgm_cadv_done3

; #define RAWBAR() { asm volatile("s_waitcnt vmcnt(0) lgkmcnt(0)" ::: "memory"); __builtin_amdgcn_s_barrier(); }
;     ...
;   if (V != 1) GLDS(0, 0);
;   RAWBAR();
;   for (int kt = 0; kt < nk; kt += 2) {
;     if (V != 1) GLDS(kt + 1, 1);
;     if (V != 2) COMPUTE(0);
;     RAWBAR();
;     if (V != 1) if (kt + 2 < nk) GLDS(kt + 2, 0);
;     if (V != 2) COMPUTE(1);
;     RAWBAR();
.Lgm_cadv_done3:
	s_waitcnt lgkmcnt(8)
	v_mfma_f32_16x16x32_bf16 v[0:3], v[162:165], v[128:131], v[0:3]
	v_mfma_f32_16x16x32_bf16 v[4:7], v[166:169], v[128:131], v[4:7]
	v_mfma_f32_16x16x32_bf16 v[8:11], v[170:173], v[128:131], v[8:11]
	v_mfma_f32_16x16x32_bf16 v[12:15], v[174:177], v[128:131], v[12:15]
	ds_read_b128 v[128:131], v207
	v_mfma_f32_16x16x32_bf16 v[16:19], v[162:165], v[132:135], v[16:19]
	v_mfma_f32_16x16x32_bf16 v[20:23], v[166:169], v[132:135], v[20:23]
	v_mfma_f32_16x16x32_bf16 v[24:27], v[170:173], v[132:135], v[24:27]
	v_mfma_f32_16x16x32_bf16 v[28:31], v[174:177], v[132:135], v[28:31]
	ds_read_b128 v[132:135], v207 offset:2048
	v_mfma_f32_16x16x32_bf16 v[32:35], v[162:165], v[136:139], v[32:35]
	v_mfma_f32_16x16x32_bf16 v[36:39], v[166:169], v[136:139], v[36:39]
	v_mfma_f32_16x16x32_bf16 v[40:43], v[170:173], v[136:139], v[40:43]
	v_mfma_f32_16x16x32_bf16 v[44:47], v[174:177], v[136:139], v[44:47]
	ds_read_b128 v[136:139], v207 offset:4096
	v_mfma_f32_16x16x32_bf16 v[48:51], v[162:165], v[140:143], v[48:51]
	v_mfma_f32_16x16x32_bf16 v[52:55], v[166:169], v[140:143], v[52:55]
	v_mfma_f32_16x16x32_bf16 v[56:59], v[170:173], v[140:143], v[56:59]
	v_mfma_f32_16x16x32_bf16 v[60:63], v[174:177], v[140:143], v[60:63]
	ds_read_b128 v[140:143], v207 offset:6144
	s_waitcnt lgkmcnt(8)
	v_mfma_f32_16x16x32_bf16 v[64:67], v[162:165], v[144:147], v[64:67]
	v_mfma_f32_16x16x32_bf16 v[68:71], v[166:169], v[144:147], v[68:71]
	v_mfma_f32_16x16x32_bf16 v[72:75], v[170:173], v[144:147], v[72:75]
	v_mfma_f32_16x16x32_bf16 v[76:79], v[174:177], v[144:147], v[76:79]
	ds_read_b128 v[144:147], v207 offset:8192
	v_mfma_f32_16x16x32_bf16 v[80:83], v[162:165], v[148:151], v[80:83]
	v_mfma_f32_16x16x32_bf16 v[84:87], v[166:169], v[148:151], v[84:87]
	v_mfma_f32_16x16x32_bf16 v[88:91], v[170:173], v[148:151], v[88:91]
	v_mfma_f32_16x16x32_bf16 v[92:95], v[174:177], v[148:151], v[92:95]
	ds_read_b128 v[148:151], v207 offset:10240
	v_mfma_f32_16x16x32_bf16 v[96:99], v[162:165], v[152:155], v[96:99]
	v_mfma_f32_16x16x32_bf16 v[100:103], v[166:169], v[152:155], v[100:103]
	v_mfma_f32_16x16x32_bf16 v[104:107], v[170:173], v[152:155], v[104:107]
	v_mfma_f32_16x16x32_bf16 v[108:111], v[174:177], v[152:155], v[108:111]
	ds_read_b128 v[152:155], v207 offset:12288
	v_mfma_f32_16x16x32_bf16 v[112:115], v[162:165], v[156:159], v[112:115]
	v_mfma_f32_16x16x32_bf16 v[116:119], v[166:169], v[156:159], v[116:119]
	v_mfma_f32_16x16x32_bf16 v[120:123], v[170:173], v[156:159], v[120:123]
	v_mfma_f32_16x16x32_bf16 v[124:127], v[174:177], v[156:159], v[124:127]
	ds_read_b128 v[156:159], v207 offset:14336
	s_waitcnt lgkmcnt(4)
	v_mfma_f32_16x16x32_bf16 v[0:3], v[224:227], v[128:131], v[0:3]
	v_mfma_f32_16x16x32_bf16 v[4:7], v[228:231], v[128:131], v[4:7]
	v_mfma_f32_16x16x32_bf16 v[8:11], v[232:235], v[128:131], v[8:11]
	v_mfma_f32_16x16x32_bf16 v[12:15], v[236:239], v[128:131], v[12:15]
	v_mfma_f32_16x16x32_bf16 v[16:19], v[224:227], v[132:135], v[16:19]
	v_mfma_f32_16x16x32_bf16 v[20:23], v[228:231], v[132:135], v[20:23]
	v_mfma_f32_16x16x32_bf16 v[24:27], v[232:235], v[132:135], v[24:27]
	v_mfma_f32_16x16x32_bf16 v[28:31], v[236:239], v[132:135], v[28:31]
	s_waitcnt vmcnt(0) lgkmcnt(0)
	s_barrier
	ds_read_b128 v[162:165], v208
	ds_read_b128 v[166:169], v208 offset:2048
	ds_read_b128 v[170:173], v208 offset:4096
	ds_read_b128 v[174:177], v208 offset:6144
	ds_read_b128 v[128:131], v204
	ds_read_b128 v[132:135], v204 offset:2048
	s_add_u32 m0, s14, 0x10000
	v_mfma_f32_16x16x32_bf16 v[32:35], v[224:227], v[136:139], v[32:35]
	global_load_lds_dwordx4 v220, s[22:23]
	s_add_u32 m0, s14, 0x18000
	v_mfma_f32_16x16x32_bf16 v[36:39], v[228:231], v[136:139], v[36:39]
	global_load_lds_dwordx4 v220, s[24:25]
	s_add_u32 m0, s14, 0x10400
	v_mfma_f32_16x16x32_bf16 v[40:43], v[232:235], v[136:139], v[40:43]
	global_load_lds_dwordx4 v221, s[22:23]
	s_add_u32 m0, s14, 0x18400
	v_mfma_f32_16x16x32_bf16 v[44:47], v[236:239], v[136:139], v[44:47]
	global_load_lds_dwordx4 v221, s[24:25]
	ds_read_b128 v[136:139], v204 offset:4096
	s_add_u32 m0, s14, 0x10800
	v_mfma_f32_16x16x32_bf16 v[48:51], v[224:227], v[140:143], v[48:51]
	global_load_lds_dwordx4 v222, s[22:23]
	s_add_u32 m0, s14, 0x18800
	v_mfma_f32_16x16x32_bf16 v[52:55], v[228:231], v[140:143], v[52:55]
	global_load_lds_dwordx4 v222, s[24:25]
	s_add_u32 m0, s14, 0x10c00
	v_mfma_f32_16x16x32_bf16 v[56:59], v[232:235], v[140:143], v[56:59]
	global_load_lds_dwordx4 v223, s[22:23]
	s_add_u32 m0, s14, 0x18c00
	v_mfma_f32_16x16x32_bf16 v[60:63], v[236:239], v[140:143], v[60:63]
	global_load_lds_dwordx4 v223, s[24:25]
	ds_read_b128 v[140:143], v204 offset:6144
	v_mfma_f32_16x16x32_bf16 v[64:67], v[224:227], v[144:147], v[64:67]
	v_mfma_f32_16x16x32_bf16 v[68:71], v[228:231], v[144:147], v[68:71]
	v_mfma_f32_16x16x32_bf16 v[72:75], v[232:235], v[144:147], v[72:75]
	v_mfma_f32_16x16x32_bf16 v[76:79], v[236:239], v[144:147], v[76:79]
	ds_read_b128 v[144:147], v204 offset:8192
	v_mfma_f32_16x16x32_bf16 v[80:83], v[224:227], v[148:151], v[80:83]
	v_mfma_f32_16x16x32_bf16 v[84:87], v[228:231], v[148:151], v[84:87]
	v_mfma_f32_16x16x32_bf16 v[88:91], v[232:235], v[148:151], v[88:91]
	v_mfma_f32_16x16x32_bf16 v[92:95], v[236:239], v[148:151], v[92:95]
	ds_read_b128 v[148:151], v204 offset:10240
	v_mfma_f32_16x16x32_bf16 v[96:99], v[224:227], v[152:155], v[96:99]
	v_mfma_f32_16x16x32_bf16 v[100:103], v[228:231], v[152:155], v[100:103]
	v_mfma_f32_16x16x32_bf16 v[104:107], v[232:235], v[152:155], v[104:107]
	v_mfma_f32_16x16x32_bf16 v[108:111], v[236:239], v[152:155], v[108:111]
	ds_read_b128 v[152:155], v204 offset:12288
	v_mfma_f32_16x16x32_bf16 v[112:115], v[224:227], v[156:159], v[112:115]
	v_mfma_f32_16x16x32_bf16 v[116:119], v[228:231], v[156:159], v[116:119]
	v_mfma_f32_16x16x32_bf16 v[120:123], v[232:235], v[156:159], v[120:123]
	v_mfma_f32_16x16x32_bf16 v[124:127], v[236:239], v[156:159], v[124:127]
	ds_read_b128 v[156:159], v204 offset:14336
	ds_read_b128 v[224:227], v209
	ds_read_b128 v[228:231], v209 offset:2048
	ds_read_b128 v[232:235], v209 offset:4096
	ds_read_b128 v[236:239], v209 offset:6144
	s_add_u32 s22, s22, 0x80
	s_addc_u32 s23, s23, 0
	s_add_u32 s24, s24, 0x80
	s_addc_u32 s25, s25, 0
	s_add_u32 s26, s26, 1
	s_cmp_eq_u32 s26, s50
	s_cbranch_scc0 .Lgm_cadv_done4
	s_mov_b32 s26, 0
	s_add_u32 s27, s27, s30
	s_cmp_lt_u32 s27, s29
	s_cbranch_scc1 .Lgm_cadv_new4
	s_lshl_b32 s53, s50, 7
	s_sub_u32 s22, s22, s53
	s_subb_u32 s23, s23, 0
	s_sub_u32 s24, s24, s53
	s_subb_u32 s25, s25, 0
	s_branch .Lgm_cadv_done4

; #define RAWBAR() { asm volatile("s_waitcnt vmcnt(0) lgkmcnt(0)" ::: "memory"); __builtin_amdgcn_s_barrier(); }
;     ...
;   if (V != 1) GLDS(0, 0);
;   RAWBAR();
;   for (int kt = 0; kt < nk; kt += 2) {
;     if (V != 1) GLDS(kt + 1, 1);
;     if (V != 2) COMPUTE(0);
;     RAWBAR();
;     if (V != 1) if (kt + 2 < nk) GLDS(kt + 2, 0);
;     if (V != 2) COMPUTE(1);
;     RAWBAR();
.Lgm_pair:
	s_waitcnt lgkmcnt(8)
	v_mfma_f32_16x16x32_bf16 v[0:3], v[162:165], v[128:131], v[0:3]
	v_mfma_f32_16x16x32_bf16 v[4:7], v[166:169], v[128:131], v[4:7]
	v_mfma_f32_16x16x32_bf16 v[8:11], v[170:173], v[128:131], v[8:11]
	v_mfma_f32_16x16x32_bf16 v[12:15], v[174:177], v[128:131], v[12:15]
	ds_read_b128 v[128:131], v205
	v_mfma_f32_16x16x32_bf16 v[16:19], v[162:165], v[132:135], v[16:19]
	v_mfma_f32_16x16x32_bf16 v[20:23], v[166:169], v[132:135], v[20:23]
	v_mfma_f32_16x16x32_bf16 v[24:27], v[170:173], v[132:135], v[24:27]
	v_mfma_f32_16x16x32_bf16 v[28:31], v[174:177], v[132:135], v[28:31]
	ds_read_b128 v[132:135], v205 offset:2048
	v_mfma_f32_16x16x32_bf16 v[32:35], v[162:165], v[136:139], v[32:35]
	v_mfma_f32_16x16x32_bf16 v[36:39], v[166:169], v[136:139], v[36:39]
	v_mfma_f32_16x16x32_bf16 v[40:43], v[170:173], v[136:139], v[40:43]
	v_mfma_f32_16x16x32_bf16 v[44:47], v[174:177], v[136:139], v[44:47]
	ds_read_b128 v[136:139], v205 offset:4096
	v_mfma_f32_16x16x32_bf16 v[48:51], v[162:165], v[140:143], v[48:51]
	v_mfma_f32_16x16x32_bf16 v[52:55], v[166:169], v[140:143], v[52:55]
	v_mfma_f32_16x16x32_bf16 v[56:59], v[170:173], v[140:143], v[56:59]
	v_mfma_f32_16x16x32_bf16 v[60:63], v[174:177], v[140:143], v[60:63]
	ds_read_b128 v[140:143], v205 offset:6144
	s_waitcnt lgkmcnt(8)
	v_mfma_f32_16x16x32_bf16 v[64:67], v[162:165], v[144:147], v[64:67]
	v_mfma_f32_16x16x32_bf16 v[68:71], v[166:169], v[144:147], v[68:71]
	v_mfma_f32_16x16x32_bf16 v[72:75], v[170:173], v[144:147], v[72:75]
	v_mfma_f32_16x16x32_bf16 v[76:79], v[174:177], v[144:147], v[76:79]
	ds_read_b128 v[144:147], v205 offset:8192
	v_mfma_f32_16x16x32_bf16 v[80:83], v[162:165], v[148:151], v[80:83]
	v_mfma_f32_16x16x32_bf16 v[84:87], v[166:169], v[148:151], v[84:87]
	v_mfma_f32_16x16x32_bf16 v[88:91], v[170:173], v[148:151], v[88:91]
	v_mfma_f32_16x16x32_bf16 v[92:95], v[174:177], v[148:151], v[92:95]
	ds_read_b128 v[148:151], v205 offset:10240
	v_mfma_f32_16x16x32_bf16 v[96:99], v[162:165], v[152:155], v[96:99]
	v_mfma_f32_16x16x32_bf16 v[100:103], v[166:169], v[152:155], v[100:103]
	v_mfma_f32_16x16x32_bf16 v[104:107], v[170:173], v[152:155], v[104:107]
	v_mfma_f32_16x16x32_bf16 v[108:111], v[174:177], v[152:155], v[108:111]
	ds_read_b128 v[152:155], v205 offset:12288
	v_mfma_f32_16x16x32_bf16 v[112:115], v[162:165], v[156:159], v[112:115]
	v_mfma_f32_16x16x32_bf16 v[116:119], v[166:169], v[156:159], v[116:119]
	v_mfma_f32_16x16x32_bf16 v[120:123], v[170:173], v[156:159], v[120:123]
	v_mfma_f32_16x16x32_bf16 v[124:127], v[174:177], v[156:159], v[124:127]
	ds_read_b128 v[156:159], v205 offset:14336
	s_waitcnt lgkmcnt(4)
	v_mfma_f32_16x16x32_bf16 v[0:3], v[224:227], v[128:131], v[0:3]
	v_mfma_f32_16x16x32_bf16 v[4:7], v[228:231], v[128:131], v[4:7]
	v_mfma_f32_16x16x32_bf16 v[8:11], v[232:235], v[128:131], v[8:11]
	v_mfma_f32_16x16x32_bf16 v[12:15], v[236:239], v[128:131], v[12:15]
	v_mfma_f32_16x16x32_bf16 v[16:19], v[224:227], v[132:135], v[16:19]
	v_mfma_f32_16x16x32_bf16 v[20:23], v[228:231], v[132:135], v[20:23]
	v_mfma_f32_16x16x32_bf16 v[24:27], v[232:235], v[132:135], v[24:27]
	v_mfma_f32_16x16x32_bf16 v[28:31], v[236:239], v[132:135], v[28:31]
	s_waitcnt vmcnt(0) lgkmcnt(0)
	s_barrier
	ds_read_b128 v[162:165], v210
	ds_read_b128 v[166:169], v210 offset:2048
	ds_read_b128 v[170:173], v210 offset:4096
	ds_read_b128 v[174:177], v210 offset:6144
	ds_read_b128 v[128:131], v206
	ds_read_b128 v[132:135], v206 offset:2048
	s_add_u32 m0, s14, 0x0
	v_mfma_f32_16x16x32_bf16 v[32:35], v[224:227], v[136:139], v[32:35]
	global_load_lds_dwordx4 v220, s[22:23]
	s_add_u32 m0, s14, 0x8000
	v_mfma_f32_16x16x32_bf16 v[36:39], v[228:231], v[136:139], v[36:39]
	global_load_lds_dwordx4 v220, s[24:25]
	s_add_u32 m0, s14, 0x400
	v_mfma_f32_16x16x32_bf16 v[40:43], v[232:235], v[136:139], v[40:43]
	global_load_lds_dwordx4 v221, s[22:23]
	s_add_u32 m0, s14, 0x8400
	v_mfma_f32_16x16x32_bf16 v[44:47], v[236:239], v[136:139], v[44:47]
	global_load_lds_dwordx4 v221, s[24:25]
	ds_read_b128 v[136:139], v206 offset:4096
	s_add_u32 m0, s14, 0x800
	v_mfma_f32_16x16x32_bf16 v[48:51], v[224:227], v[140:143], v[48:51]
	global_load_lds_dwordx4 v222, s[22:23]
	s_add_u32 m0, s14, 0x8800
	v_mfma_f32_16x16x32_bf16 v[52:55], v[228:231], v[140:143], v[52:55]
	global_load_lds_dwordx4 v222, s[24:25]
	s_add_u32 m0, s14, 0xc00
	v_mfma_f32_16x16x32_bf16 v[56:59], v[232:235], v[140:143], v[56:59]
	global_load_lds_dwordx4 v223, s[22:23]
	s_add_u32 m0, s14, 0x8c00
	v_mfma_f32_16x16x32_bf16 v[60:63], v[236:239], v[140:143], v[60:63]
	global_load_lds_dwordx4 v223, s[24:25]
	ds_read_b128 v[140:143], v206 offset:6144
	v_mfma_f32_16x16x32_bf16 v[64:67], v[224:227], v[144:147], v[64:67]
	v_mfma_f32_16x16x32_bf16 v[68:71], v[228:231], v[144:147], v[68:71]
	v_mfma_f32_16x16x32_bf16 v[72:75], v[232:235], v[144:147], v[72:75]
	v_mfma_f32_16x16x32_bf16 v[76:79], v[236:239], v[144:147], v[76:79]
	ds_read_b128 v[144:147], v206 offset:8192
	v_mfma_f32_16x16x32_bf16 v[80:83], v[224:227], v[148:151], v[80:83]
	v_mfma_f32_16x16x32_bf16 v[84:87], v[228:231], v[148:151], v[84:87]
	v_mfma_f32_16x16x32_bf16 v[88:91], v[232:235], v[148:151], v[88:91]
	v_mfma_f32_16x16x32_bf16 v[92:95], v[236:239], v[148:151], v[92:95]
	ds_read_b128 v[148:151], v206 offset:10240
	v_mfma_f32_16x16x32_bf16 v[96:99], v[224:227], v[152:155], v[96:99]
	v_mfma_f32_16x16x32_bf16 v[100:103], v[228:231], v[152:155], v[100:103]
	v_mfma_f32_16x16x32_bf16 v[104:107], v[232:235], v[152:155], v[104:107]
	v_mfma_f32_16x16x32_bf16 v[108:111], v[236:239], v[152:155], v[108:111]
	ds_read_b128 v[152:155], v206 offset:12288
	v_mfma_f32_16x16x32_bf16 v[112:115], v[224:227], v[156:159], v[112:115]
	v_mfma_f32_16x16x32_bf16 v[116:119], v[228:231], v[156:159], v[116:119]
	v_mfma_f32_16x16x32_bf16 v[120:123], v[232:235], v[156:159], v[120:123]
	v_mfma_f32_16x16x32_bf16 v[124:127], v[236:239], v[156:159], v[124:127]
	ds_read_b128 v[156:159], v206 offset:14336
	ds_read_b128 v[224:227], v211
	ds_read_b128 v[228:231], v211 offset:2048
	ds_read_b128 v[232:235], v211 offset:4096
	ds_read_b128 v[236:239], v211 offset:6144
	s_add_u32 s22, s22, 0x80
	s_addc_u32 s23, s23, 0
	s_add_u32 s24, s24, 0x80
	s_addc_u32 s25, s25, 0
	s_add_u32 s26, s26, 1
	s_cmp_eq_u32 s26, s50
	s_cbranch_scc0 .Lgm_cadv_done5
	s_mov_b32 s26, 0
	s_add_u32 s27, s27, s30
	s_cmp_lt_u32 s27, s29
	s_cbranch_scc1 .Lgm_cadv_new5
	s_lshl_b32 s53, s50, 7
	s_sub_u32 s22, s22, s53
	s_subb_u32 s23, s23, 0
	s_sub_u32 s24, s24, s53
	s_subb_u32 s25, s25, 0
	s_branch .Lgm_cadv_done5

; #define RAWBAR() { asm volatile("s_waitcnt vmcnt(0) lgkmcnt(0)" ::: "memory"); __builtin_amdgcn_s_barrier(); }
;     ...
;   if (V != 1) GLDS(0, 0);
;   RAWBAR();
;   for (int kt = 0; kt < nk; kt += 2) {
;     if (V != 1) GLDS(kt + 1, 1);
;     if (V != 2) COMPUTE(0);
;     RAWBAR();
;     if (V != 1) if (kt + 2 < nk) GLDS(kt + 2, 0);
;     if (V != 2) COMPUTE(1);
;     RAWBAR();
.Lgm_cadv_done7:
	s_waitcnt lgkmcnt(8)
	v_mfma_f32_16x16x32_bf16 v[0:3], v[162:165], v[128:131], v[0:3]
	v_mfma_f32_16x16x32_bf16 v[4:7], v[166:169], v[128:131], v[4:7]
	v_mfma_f32_16x16x32_bf16 v[8:11], v[170:173], v[128:131], v[8:11]
	v_mfma_f32_16x16x32_bf16 v[12:15], v[174:177], v[128:131], v[12:15]
	ds_read_b128 v[128:131], v207
	v_mfma_f32_16x16x32_bf16 v[16:19], v[162:165], v[132:135], v[16:19]
	v_mfma_f32_16x16x32_bf16 v[20:23], v[166:169], v[132:135], v[20:23]
	v_mfma_f32_16x16x32_bf16 v[24:27], v[170:173], v[132:135], v[24:27]
	v_mfma_f32_16x16x32_bf16 v[28:31], v[174:177], v[132:135], v[28:31]
	ds_read_b128 v[132:135], v207 offset:2048
	v_mfma_f32_16x16x32_bf16 v[32:35], v[162:165], v[136:139], v[32:35]
	v_mfma_f32_16x16x32_bf16 v[36:39], v[166:169], v[136:139], v[36:39]
	v_mfma_f32_16x16x32_bf16 v[40:43], v[170:173], v[136:139], v[40:43]
	v_mfma_f32_16x16x32_bf16 v[44:47], v[174:177], v[136:139], v[44:47]
	ds_read_b128 v[136:139], v207 offset:4096
	v_mfma_f32_16x16x32_bf16 v[48:51], v[162:165], v[140:143], v[48:51]
	v_mfma_f32_16x16x32_bf16 v[52:55], v[166:169], v[140:143], v[52:55]
	v_mfma_f32_16x16x32_bf16 v[56:59], v[170:173], v[140:143], v[56:59]
	v_mfma_f32_16x16x32_bf16 v[60:63], v[174:177], v[140:143], v[60:63]
	ds_read_b128 v[140:143], v207 offset:6144
	s_waitcnt lgkmcnt(8)
	v_mfma_f32_16x16x32_bf16 v[64:67], v[162:165], v[144:147], v[64:67]
	v_mfma_f32_16x16x32_bf16 v[68:71], v[166:169], v[144:147], v[68:71]
	v_mfma_f32_16x16x32_bf16 v[72:75], v[170:173], v[144:147], v[72:75]
	v_mfma_f32_16x16x32_bf16 v[76:79], v[174:177], v[144:147], v[76:79]
	ds_read_b128 v[144:147], v207 offset:8192
	v_mfma_f32_16x16x32_bf16 v[80:83], v[162:165], v[148:151], v[80:83]
	v_mfma_f32_16x16x32_bf16 v[84:87], v[166:169], v[148:151], v[84:87]
	v_mfma_f32_16x16x32_bf16 v[88:91], v[170:173], v[148:151], v[88:91]
	v_mfma_f32_16x16x32_bf16 v[92:95], v[174:177], v[148:151], v[92:95]
	ds_read_b128 v[148:151], v207 offset:10240
	v_mfma_f32_16x16x32_bf16 v[96:99], v[162:165], v[152:155], v[96:99]
	v_mfma_f32_16x16x32_bf16 v[100:103], v[166:169], v[152:155], v[100:103]
	v_mfma_f32_16x16x32_bf16 v[104:107], v[170:173], v[152:155], v[104:107]
	v_mfma_f32_16x16x32_bf16 v[108:111], v[174:177], v[152:155], v[108:111]
	ds_read_b128 v[152:155], v207 offset:12288
	v_mfma_f32_16x16x32_bf16 v[112:115], v[162:165], v[156:159], v[112:115]
	v_mfma_f32_16x16x32_bf16 v[116:119], v[166:169], v[156:159], v[116:119]
	v_mfma_f32_16x16x32_bf16 v[120:123], v[170:173], v[156:159], v[120:123]
	v_mfma_f32_16x16x32_bf16 v[124:127], v[174:177], v[156:159], v[124:127]
	ds_read_b128 v[156:159], v207 offset:14336
	s_waitcnt lgkmcnt(4)
	v_mfma_f32_16x16x32_bf16 v[0:3], v[224:227], v[128:131], v[0:3]
	v_mfma_f32_16x16x32_bf16 v[4:7], v[228:231], v[128:131], v[4:7]
	v_mfma_f32_16x16x32_bf16 v[8:11], v[232:235], v[128:131], v[8:11]
	v_mfma_f32_16x16x32_bf16 v[12:15], v[236:239], v[128:131], v[12:15]
	v_mfma_f32_16x16x32_bf16 v[16:19], v[224:227], v[132:135], v[16:19]
	v_mfma_f32_16x16x32_bf16 v[20:23], v[228:231], v[132:135], v[20:23]
	v_mfma_f32_16x16x32_bf16 v[24:27], v[232:235], v[132:135], v[24:27]
	v_mfma_f32_16x16x32_bf16 v[28:31], v[236:239], v[132:135], v[28:31]
	s_waitcnt vmcnt(0) lgkmcnt(0)
	s_barrier
	ds_read_b128 v[162:165], v208
	ds_read_b128 v[166:169], v208 offset:2048
	ds_read_b128 v[170:173], v208 offset:4096
	ds_read_b128 v[174:177], v208 offset:6144
	ds_read_b128 v[128:131], v204
	ds_read_b128 v[132:135], v204 offset:2048
	s_add_u32 m0, s14, 0x10000
	v_mfma_f32_16x16x32_bf16 v[32:35], v[224:227], v[136:139], v[32:35]
	global_load_lds_dwordx4 v220, s[22:23]
	s_add_u32 m0, s14, 0x10400
	v_mfma_f32_16x16x32_bf16 v[36:39], v[228:231], v[136:139], v[36:39]
	global_load_lds_dwordx4 v221, s[22:23]
	s_add_u32 m0, s14, 0x10800
	v_mfma_f32_16x16x32_bf16 v[40:43], v[232:235], v[136:139], v[40:43]
	global_load_lds_dwordx4 v222, s[22:23]
	s_add_u32 m0, s14, 0x10c00
	v_mfma_f32_16x16x32_bf16 v[44:47], v[236:239], v[136:139], v[44:47]
	global_load_lds_dwordx4 v223, s[22:23]
	ds_read_b128 v[136:139], v204 offset:4096
	v_mfma_f32_16x16x32_bf16 v[48:51], v[224:227], v[140:143], v[48:51]
	v_mfma_f32_16x16x32_bf16 v[52:55], v[228:231], v[140:143], v[52:55]
	v_mfma_f32_16x16x32_bf16 v[56:59], v[232:235], v[140:143], v[56:59]
	v_mfma_f32_16x16x32_bf16 v[60:63], v[236:239], v[140:143], v[60:63]
	ds_read_b128 v[140:143], v204 offset:6144
	v_mfma_f32_16x16x32_bf16 v[64:67], v[224:227], v[144:147], v[64:67]
	v_mfma_f32_16x16x32_bf16 v[68:71], v[228:231], v[144:147], v[68:71]
	v_mfma_f32_16x16x32_bf16 v[72:75], v[232:235], v[144:147], v[72:75]
	v_mfma_f32_16x16x32_bf16 v[76:79], v[236:239], v[144:147], v[76:79]
	ds_read_b128 v[144:147], v204 offset:8192
	v_mfma_f32_16x16x32_bf16 v[80:83], v[224:227], v[148:151], v[80:83]
	v_mfma_f32_16x16x32_bf16 v[84:87], v[228:231], v[148:151], v[84:87]
	v_mfma_f32_16x16x32_bf16 v[88:91], v[232:235], v[148:151], v[88:91]
	v_mfma_f32_16x16x32_bf16 v[92:95], v[236:239], v[148:151], v[92:95]
	ds_read_b128 v[148:151], v204 offset:10240
	v_mfma_f32_16x16x32_bf16 v[96:99], v[224:227], v[152:155], v[96:99]
	v_mfma_f32_16x16x32_bf16 v[100:103], v[228:231], v[152:155], v[100:103]
	v_mfma_f32_16x16x32_bf16 v[104:107], v[232:235], v[152:155], v[104:107]
	v_mfma_f32_16x16x32_bf16 v[108:111], v[236:239], v[152:155], v[108:111]
	ds_read_b128 v[152:155], v204 offset:12288
	v_mfma_f32_16x16x32_bf16 v[112:115], v[224:227], v[156:159], v[112:115]
	v_mfma_f32_16x16x32_bf16 v[116:119], v[228:231], v[156:159], v[116:119]
	v_mfma_f32_16x16x32_bf16 v[120:123], v[232:235], v[156:159], v[120:123]
	v_mfma_f32_16x16x32_bf16 v[124:127], v[236:239], v[156:159], v[124:127]
	ds_read_b128 v[156:159], v204 offset:14336
	ds_read_b128 v[224:227], v209
	ds_read_b128 v[228:231], v209 offset:2048
	ds_read_b128 v[232:235], v209 offset:4096
	ds_read_b128 v[236:239], v209 offset:6144
	s_lshr_b32 s53, s28, 5
	s_and_b32 s54, s28, 31
	s_lshr_b32 s55, s53, s34
	s_lshl_b32 s56, s55, s34
	s_sub_u32 s56, s53, s56
	s_lshl_b32 s55, s55, 3
	s_add_u32 s55, s55, s31
	s_lshr_b32 s57, s54, 2
	s_add_u32 s55, s55, s57
	s_lshl_b32 s56, s56, 2
	s_and_b32 s57, s54, 3
	s_add_u32 s56, s56, s57
	s_lshl_b32 s57, s55, 8
	s_add_u32 s57, s57, s58
	s_mul_i32 s57, s57, s36
	s_add_u32 s38, s12, s57
	s_addc_u32 s39, s13, 0
	s_lshl_b32 s57, s56, 9
	s_add_u32 s57, s57, s59
	s_add_u32 s38, s38, s57
	s_addc_u32 s39, s39, 0
	s_cmp_eq_u64 s[4:5], 0
	s_cbranch_scc1 .Lgm_epi_relu
; DI int crow(int r, int hf) { return (r & 3) + 8 * (r >> 2) + 4 * hf; }
;     ...
;     gemm_tile<V>(A + (size_t)m0 * lda, lda, K / 64, nullptr, 0, 0, Wt + (size_t)n0 * ldb, ldb, smem, [&](f32x16(&acc)[2][2], int moff) {
;       const int m0_ = m0 + moff;
;       int l32_ = l32, hf_ = hf; asm volatile("" : "+v"(l32_), "+v"(hf_));
; #pragma unroll
;       for (int i = 0; i < 2; ++i)
; #pragma unroll
;         for (int j = 0; j < 2; ++j)
; #pragma unroll
;           for (int r = 0; r < 16; ++r) {
;             const int row = m0_ + wm * 64 + i * 32 + crow(r, hf_), col = n0 + wn * 64 + j * 32 + l32_;
;             float v = acc[i][j][r];
;             if (mode == 1) { v = fmaxf(v, 0.f); v = v * v; }
;             if (V == 0 || v == 123456.789f) C[(size_t)row * ldc + col] = f2bf(v);
;           }
;     });
	v_cvt_pk_bf16_f32 v240, v0, v1
	v_cvt_pk_bf16_f32 v241, v2, v3
	ds_write_b64 v178, v[240:241] offset:32768
	v_cvt_pk_bf16_f32 v242, v4, v5
	v_cvt_pk_bf16_f32 v243, v6, v7
	ds_write_b64 v179, v[242:243] offset:32768
	v_cvt_pk_bf16_f32 v244, v8, v9
	v_cvt_pk_bf16_f32 v245, v10, v11
	ds_write_b64 v180, v[244:245] offset:32768
	v_cvt_pk_bf16_f32 v246, v12, v13
	v_cvt_pk_bf16_f32 v247, v14, v15
	ds_write_b64 v181, v[246:247] offset:32768
	v_cvt_pk_bf16_f32 v240, v16, v17
	v_cvt_pk_bf16_f32 v241, v18, v19
	ds_write_b64 v178, v[240:241] offset:34816
	v_cvt_pk_bf16_f32 v242, v20, v21
	v_cvt_pk_bf16_f32 v243, v22, v23
	ds_write_b64 v179, v[242:243] offset:34816
	v_cvt_pk_bf16_f32 v244, v24, v25
	v_cvt_pk_bf16_f32 v245, v26, v27
	ds_write_b64 v180, v[244:245] offset:34816
	v_cvt_pk_bf16_f32 v246, v28, v29
	v_cvt_pk_bf16_f32 v247, v30, v31
	ds_write_b64 v181, v[246:247] offset:34816
	ds_read_b128 v[0:3], v194 offset:32768
	ds_read_b128 v[4:7], v188 offset:33792
	ds_read_b128 v[8:11], v194 offset:34816
	ds_read_b128 v[12:15], v188 offset:35840
	v_cvt_pk_bf16_f32 v240, v32, v33
	v_cvt_pk_bf16_f32 v241, v34, v35
	ds_write_b64 v178, v[240:241] offset:32768
	v_cvt_pk_bf16_f32 v242, v36, v37
	v_cvt_pk_bf16_f32 v243, v38, v39
	ds_write_b64 v179, v[242:243] offset:32768
	v_cvt_pk_bf16_f32 v244, v40, v41
	v_cvt_pk_bf16_f32 v245, v42, v43
	ds_write_b64 v180, v[244:245] offset:32768
	v_cvt_pk_bf16_f32 v246, v44, v45
	v_cvt_pk_bf16_f32 v247, v46, v47
	ds_write_b64 v181, v[246:247] offset:32768
	v_cvt_pk_bf16_f32 v240, v48, v49
	v_cvt_pk_bf16_f32 v241, v50, v51
	ds_write_b64 v178, v[240:241] offset:34816
	v_cvt_pk_bf16_f32 v242, v52, v53
	v_cvt_pk_bf16_f32 v243, v54, v55
	ds_write_b64 v179, v[242:243] offset:34816
	v_cvt_pk_bf16_f32 v244, v56, v57
	v_cvt_pk_bf16_f32 v245, v58, v59
	ds_write_b64 v180, v[244:245] offset:34816
	v_cvt_pk_bf16_f32 v246, v60, v61
	v_cvt_pk_bf16_f32 v247, v62, v63
	ds_write_b64 v181, v[246:247] offset:34816
	ds_read_b128 v[32:35], v194 offset:32768
	ds_read_b128 v[36:39], v188 offset:33792
	ds_read_b128 v[40:43], v194 offset:34816
	ds_read_b128 v[44:47], v188 offset:35840
	s_waitcnt lgkmcnt(12)
	global_store_dwordx4 v195, v[0:3], s[38:39]
	s_add_u32 s38, s38, s40
	s_addc_u32 s39, s39, 0
	global_store_dwordx4 v195, v[4:7], s[38:39]
	s_add_u32 s38, s38, s40
	s_addc_u32 s39, s39, 0
	global_store_dwordx4 v195, v[8:11], s[38:39]
	s_add_u32 s38, s38, s40
	s_addc_u32 s39, s39, 0
	global_store_dwordx4 v195, v[12:15], s[38:39]
	s_add_u32 s38, s38, s40
	s_addc_u32 s39, s39, 0
	v_cvt_pk_bf16_f32 v240, v64, v65
	v_cvt_pk_bf16_f32 v241, v66, v67
	ds_write_b64 v178, v[240:241] offset:32768
	v_cvt_pk_bf16_f32 v242, v68, v69
	v_cvt_pk_bf16_f32 v243, v70, v71
	ds_write_b64 v179, v[242:243] offset:32768
	v_cvt_pk_bf16_f32 v244, v72, v73
	v_cvt_pk_bf16_f32 v245, v74, v75
	ds_write_b64 v180, v[244:245] offset:32768
	v_cvt_pk_bf16_f32 v246, v76, v77
	v_cvt_pk_bf16_f32 v247, v78, v79
	ds_write_b64 v181, v[246:247] offset:32768
	v_cvt_pk_bf16_f32 v240, v80, v81
	v_cvt_pk_bf16_f32 v241, v82, v83
	ds_write_b64 v178, v[240:241] offset:34816
	v_cvt_pk_bf16_f32 v242, v84, v85
	v_cvt_pk_bf16_f32 v243, v86, v87
	ds_write_b64 v179, v[242:243] offset:34816
	v_cvt_pk_bf16_f32 v244, v88, v89
	v_cvt_pk_bf16_f32 v245, v90, v91
	ds_write_b64 v180, v[244:245] offset:34816
	v_cvt_pk_bf16_f32 v246, v92, v93
	v_cvt_pk_bf16_f32 v247, v94, v95
	ds_write_b64 v181, v[246:247] offset:34816
	ds_read_b128 v[64:67], v194 offset:32768
	ds_read_b128 v[68:71], v188 offset:33792
	ds_read_b128 v[72:75], v194 offset:34816
	ds_read_b128 v[76:79], v188 offset:35840
	s_waitcnt lgkmcnt(12)
	global_store_dwordx4 v195, v[32:35], s[38:39]
	s_add_u32 s38, s38, s40
	s_addc_u32 s39, s39, 0
	global_store_dwordx4 v195, v[36:39], s[38:39]
	s_add_u32 s38, s38, s40
	s_addc_u32 s39, s39, 0
	global_store_dwordx4 v195, v[40:43], s[38:39]
	s_add_u32 s38, s38, s40
	s_addc_u32 s39, s39, 0
	global_store_dwordx4 v195, v[44:47], s[38:39]
	s_add_u32 s38, s38, s40
	s_addc_u32 s39, s39, 0
	v_cvt_pk_bf16_f32 v240, v96, v97
	v_cvt_pk_bf16_f32 v241, v98, v99
	ds_write_b64 v178, v[240:241] offset:32768
	v_cvt_pk_bf16_f32 v242, v100, v101
	v_cvt_pk_bf16_f32 v243, v102, v103
	ds_write_b64 v179, v[242:243] offset:32768
	v_cvt_pk_bf16_f32 v244, v104, v105
	v_cvt_pk_bf16_f32 v245, v106, v107
	ds_write_b64 v180, v[244:245] offset:32768
	v_cvt_pk_bf16_f32 v246, v108, v109
	v_cvt_pk_bf16_f32 v247, v110, v111
	ds_write_b64 v181, v[246:247] offset:32768
	v_cvt_pk_bf16_f32 v240, v112, v113
	v_cvt_pk_bf16_f32 v241, v114, v115
	ds_write_b64 v178, v[240:241] offset:34816
	v_cvt_pk_bf16_f32 v242, v116, v117
	v_cvt_pk_bf16_f32 v243, v118, v119
	ds_write_b64 v179, v[242:243] offset:34816
	v_cvt_pk_bf16_f32 v244, v120, v121
	v_cvt_pk_bf16_f32 v245, v122, v123
	ds_write_b64 v180, v[244:245] offset:34816
	v_cvt_pk_bf16_f32 v246, v124, v125
	v_cvt_pk_bf16_f32 v247, v126, v127
	ds_write_b64 v181, v[246:247] offset:34816
	ds_read_b128 v[96:99], v194 offset:32768
	ds_read_b128 v[100:103], v188 offset:33792
	ds_read_b128 v[104:107], v194 offset:34816
	ds_read_b128 v[108:111], v188 offset:35840
	s_waitcnt lgkmcnt(12)
	global_store_dwordx4 v195, v[64:67], s[38:39]
	s_add_u32 s38, s38, s40
	s_addc_u32 s39, s39, 0
	global_store_dwordx4 v195, v[68:71], s[38:39]
	s_add_u32 s38, s38, s40
	s_addc_u32 s39, s39, 0
	global_store_dwordx4 v195, v[72:75], s[38:39]
	s_add_u32 s38, s38, s40
	s_addc_u32 s39, s39, 0
	global_store_dwordx4 v195, v[76:79], s[38:39]
	s_add_u32 s38, s38, s40
	s_addc_u32 s39, s39, 0
	s_waitcnt lgkmcnt(0)
	global_store_dwordx4 v195, v[96:99], s[38:39]
	s_add_u32 s38, s38, s40
	s_addc_u32 s39, s39, 0
	global_store_dwordx4 v195, v[100:103], s[38:39]
	s_add_u32 s38, s38, s40
	s_addc_u32 s39, s39, 0
	global_store_dwordx4 v195, v[104:107], s[38:39]
	s_add_u32 s38, s38, s40
	s_addc_u32 s39, s39, 0
	global_store_dwordx4 v195, v[108:111], s[38:39]
	s_branch .Lgm_epi_done
